# p12 tile-to-block remap: co-resident blocks (b, b+256) take adjacent row tiles of the same weight column tile (L1 operand sharing)
# baseline (speedup 1.0000x reference)
; #define G_LOAD(RA, RB, KT) { _Pragma("unroll") for (int i = 0; i < 4; i++) { \
;       RA[i] = *(const u32x4*)(Ap + (size_t)(i * 32) * lda + (KT) * 64); RB[i] = *(const u32x4*)(Bp + (size_t)(i * 32) * ldb + (KT) * 64); } }
; template <class Epi>
; DEV void gemm_tile(const bf16_t* __restrict__ A, int lda, const bf16_t* __restrict__ Bt, int ldb, int K, int m0, int n0,
;                    Epi& epi, char* smem) {
;     ...
;   const int nk = K >> 6;
;   const int lrow = tid >> 3, lcc = tid & 7;
;   const bf16_t* Ap = A + (size_t)(m0 + lrow) * lda + lcc * 8;
;   const bf16_t* Bp = Bt + (size_t)(n0 + lrow) * ldb + lcc * 8;
;     ...
;   G_LOAD(ra0, rb0, 0);
;   G_LOAD(ra1, rb1, 1);
; DEV void phase_gemm_hgin(const Params& p, char* smem) {
;   EpiHG epi{WSP(bf16_t, L1_QH), WSP(bf16_t, L1_LF), WSP(bf16_t, L1_LB), WSP(bf16_t, L1_IH), WSP(bf16_t, L1_GH), p.in[I_HGLB]};
;   const int items = (MT / 128) * 40;
;   for (int item = blockIdx.x; item < items; item += gridDim.x) {
;     int mt = item / 40, nt = item - mt * 40;
;     gemm_tile(WSP(bf16_t, OFF_H), LDH, WSP(bf16_t, S_WHGIN), LDH, 1024, mt * 128, nt * 128, epi, smem);
;   }
.Lp12_skip:
	s_add_i32 s21, s21, s86
	s_cmpk_gt_i32 s21, 0x15ff
	s_cbranch_scc1 .LBB0_601
	s_branch .LBB0_323
.LBB0_322:
	v_readlane_b32 s0, v253, 7
	v_cvt_pk_bf16_f32 v2, v2, v3
	v_cvt_pk_bf16_f32 v3, v4, v5
	v_lshl_add_u64 v[4:5], s[6:7], 0, v[58:59]
	s_add_i32 s21, s21, s86
	s_add_i32 s20, s20, s0
	v_lshl_add_u64 v[4:5], v[4:5], 0, v[0:1]
	s_cmpk_gt_i32 s21, 0x15ff
	global_store_dwordx2 v[4:5], v[2:3], off offset:96
	s_cbranch_scc1 .LBB0_601
.LBB0_323:
	s_cmp_eq_u32 s86, 0x200
	s_cbranch_scc0 .Lp12_orig
	s_lshr_b32 s0, s21, 9
	s_and_b32 s1, s51, 0xff
	s_lshl_b32 s0, s0, 8
	s_or_b32 s0, s0, s1
	s_cmpk_lt_u32 s0, 0xa50
	s_cbranch_scc0 .Lp12_skip
	s_mul_i32 s1, s0, 1639
	s_lshr_b32 s1, s1, 16
	s_mul_i32 s12, s1, 40
	s_sub_u32 s0, s0, s12
	s_lshl_b32 s1, s1, 1
	s_lshr_b32 s12, s51, 8
	s_add_u32 s1, s1, s12
	s_mul_i32 s12, s1, 40
	s_add_u32 s12, s12, s0
	s_lshl_b32 s20, s12, 7
	s_branch .Lp12_go
.Lp12_orig:
	s_cmpk_gt_i32 s21, 0x149f
	s_cbranch_scc1 .Lp12_skip
	s_lshl_b32 s20, s21, 7
	s_mul_hi_i32 s0, s21, 0x66666667
	s_lshr_b32 s1, s0, 31
	s_ashr_i32 s0, s0, 4
	s_add_i32 s1, s0, s1
	s_mul_i32 s0, s1, 0xffffffd8
	s_add_i32 s0, s0, s21
.Lp12_go:
	v_mov_b32_e32 v140, v195
	s_lshl_b32 s12, s1, 7
	s_lshl_b32 s13, s0, 7
	v_mov_b64_e32 v[2:3], s[28:29]
	v_ashrrev_i32_e32 v18, 3, v140
	v_add_u32_e32 v19, s12, v18
	s_movk_i32 s10, 0x880
	v_lshlrev_b32_e32 v0, 4, v140
	v_add_u32_e32 v6, s13, v18
	v_mov_b64_e32 v[4:5], s[18:19]
	v_mad_i64_i32 v[2:3], s[6:7], v19, s10, v[2:3]
	v_and_b32_e32 v0, 0x70, v0
	v_mad_i64_i32 v[4:5], s[6:7], v6, s10, v[4:5]
	v_lshl_add_u64 v[2:3], v[2:3], 0, v[0:1]
	s_mov_b32 s6, 0x11000
	v_add_co_u32_e32 v6, vcc, s6, v2
	v_lshl_add_u64 v[4:5], v[4:5], 0, v[0:1]
	s_nop 0
	v_addc_co_u32_e32 v7, vcc, 0, v3, vcc
	v_add_co_u32_e32 v8, vcc, s6, v4
	s_mov_b32 s6, 0x22000
	s_nop 0
	v_addc_co_u32_e32 v9, vcc, 0, v5, vcc
	v_add_co_u32_e32 v10, vcc, s6, v2
	s_mulk_i32 s1, 0x1400
	s_nop 0
	v_addc_co_u32_e32 v11, vcc, 0, v3, vcc
	v_add_co_u32_e32 v12, vcc, s6, v4
	s_mov_b32 s6, 0x33000
	s_nop 0
	v_addc_co_u32_e32 v13, vcc, 0, v5, vcc
	s_waitcnt vmcnt(22)
	v_add_co_u32_e32 v14, vcc, s6, v2
	v_and_b32_e32 v142, 64, v140
	s_nop 0
	v_addc_co_u32_e32 v15, vcc, 0, v3, vcc
	v_add_co_u32_e32 v16, vcc, s6, v4
	v_mad_u64_u32 v[130:131], s[6:7], v18, s36, v[0:1]
	s_nop 0
	v_addc_co_u32_e32 v17, vcc, 0, v5, vcc
	global_load_dwordx4 v[66:69], v[2:3], off
	global_load_dwordx4 v[74:77], v[4:5], off
	global_load_dwordx4 v[82:85], v[6:7], off
	global_load_dwordx4 v[90:93], v[8:9], off
	global_load_dwordx4 v[98:101], v[10:11], off
	global_load_dwordx4 v[106:109], v[12:13], off
	global_load_dwordx4 v[114:117], v[14:15], off
	global_load_dwordx4 v[122:125], v[16:17], off
	global_load_dwordx4 v[70:73], v[2:3], off offset:128
	global_load_dwordx4 v[78:81], v[4:5], off offset:128
	global_load_dwordx4 v[86:89], v[6:7], off offset:128
	global_load_dwordx4 v[94:97], v[8:9], off offset:128
	global_load_dwordx4 v[102:105], v[10:11], off offset:128
	global_load_dwordx4 v[110:113], v[12:13], off offset:128
	global_load_dwordx4 v[118:121], v[14:15], off offset:128
	global_load_dwordx4 v[126:129], v[16:17], off offset:128
	v_ashrrev_i32_e32 v2, 1, v140
	v_readlane_b32 s6, v254, 0
	v_and_b32_e32 v141, 0xffffffc0, v2
	v_add_u32_e32 v2, s20, v18
	v_readlane_b32 s7, v254, 1
	v_subrev_u32_e32 v4, s1, v2
	v_and_b32_e32 v0, 7, v140
	v_mov_b64_e32 v[2:3], s[6:7]
	v_mad_i64_i32 v[132:133], s[6:7], v4, s10, v[2:3]
	v_mad_i64_i32 v[134:135], s[6:7], v19, s10, v[2:3]
	v_mov_b32_e32 v2, 0
	v_lshlrev_b32_e32 v0, 4, v0
	s_mov_b32 s1, -2
	v_mov_b32_e32 v3, v2
	v_mov_b32_e32 v4, v2
	v_mov_b32_e32 v5, v2
	v_mov_b32_e32 v6, v2
	v_mov_b32_e32 v7, v2
	v_mov_b32_e32 v8, v2
	v_mov_b32_e32 v9, v2
	v_mov_b32_e32 v10, v2
	v_mov_b32_e32 v11, v2
	v_mov_b32_e32 v12, v2
	v_mov_b32_e32 v13, v2
	v_mov_b32_e32 v14, v2
	v_mov_b32_e32 v15, v2
	v_mov_b32_e32 v16, v2
	v_mov_b32_e32 v17, v2
	v_mov_b32_e32 v18, v2
	v_mov_b32_e32 v19, v2
	v_mov_b32_e32 v20, v2
	v_mov_b32_e32 v21, v2
	s_waitcnt vmcnt(37)
	v_mov_b32_e32 v22, v2
	v_mov_b32_e32 v23, v2
	v_mov_b32_e32 v24, v2
	v_mov_b32_e32 v25, v2
	v_mov_b32_e32 v26, v2
	v_mov_b32_e32 v27, v2
	v_mov_b32_e32 v28, v2
	v_mov_b32_e32 v29, v2
	s_waitcnt vmcnt(36)
	v_mov_b32_e32 v30, v2
	v_mov_b32_e32 v31, v2
	v_mov_b32_e32 v32, v2
	v_mov_b32_e32 v33, v2
	v_mov_b32_e32 v34, v2
	v_mov_b32_e32 v35, v2
	v_mov_b32_e32 v36, v2
	v_mov_b32_e32 v37, v2
	s_waitcnt vmcnt(35)
	v_mov_b32_e32 v38, v2
	v_mov_b32_e32 v39, v2
	v_mov_b32_e32 v40, v2
	v_mov_b32_e32 v41, v2
	v_mov_b32_e32 v42, v2
	v_mov_b32_e32 v43, v2
	v_mov_b32_e32 v44, v2
	v_mov_b32_e32 v45, v2
	s_waitcnt vmcnt(34)
	v_mov_b32_e32 v46, v2
	v_mov_b32_e32 v47, v2
	v_mov_b32_e32 v48, v2
	v_mov_b32_e32 v49, v2
	v_mov_b32_e32 v50, v2
	v_mov_b32_e32 v51, v2
	v_mov_b32_e32 v52, v2
	v_mov_b32_e32 v53, v2
	s_waitcnt vmcnt(33)
	v_mov_b32_e32 v54, v2
	v_mov_b32_e32 v55, v2
	v_mov_b32_e32 v56, v2
	v_mov_b32_e32 v57, v2
	v_mov_b32_e32 v58, v2
	v_mov_b32_e32 v59, v2
	v_mov_b32_e32 v60, v2
	v_mov_b32_e32 v61, v2
	s_waitcnt vmcnt(32)
	v_mov_b32_e32 v62, v2
	v_mov_b32_e32 v63, v2
	v_mov_b32_e32 v64, v2
	v_mov_b32_e32 v65, v2
	s_branch .LBB0_325
